# w_down[l+1] f32->bf16 transposition moved from the prologue into the idle CUs (64..255) of layer l down-projection GEMM tail
# speedup vs baseline: 1.0156x; 1.0102x over previous
; #define LAS __attribute__((address_space(3)))
; #define GAS __attribute__((address_space(1)))
; DEV int lane_id() { return (int)__builtin_amdgcn_mbcnt_hi(~0u, __builtin_amdgcn_mbcnt_lo(~0u, 0u)); }
; DEV int readfirstlane_i(int v) { return __builtin_amdgcn_readfirstlane(v); }
; DEV unsigned xb_add(unsigned* p, unsigned v) { return __hip_atomic_fetch_add(p, v, __ATOMIC_RELAXED, __HIP_MEMORY_SCOPE_AGENT); }
; DEV unsigned xb_xcc_id() { return (unsigned)__builtin_amdgcn_s_getreg((3 << 11) | 20) & 0xFu; }
; DEV XcdBarrier xcd_barrier_post(unsigned* bar, volatile LAS unsigned* st, int wave) {
;     XcdBarrier b; b.wave = wave; b.bar = bar; b.x = (unsigned)readfirstlane_i((int)xb_xcc_id()); b.st = st;
;     if (wave == 0 && lane_id() == 0) (void)xb_add(&bar[XB_XCNT(b.x)], 1u);
; __global__ void __launch_bounds__(NTHREADS, 2) mega_fwd(Args args) {
;     ...
;     Frame F;
;     F.in = args.in; F.out = (GAS float*)args.out; F.ws = (GAS unsigned char*)args.ws; F.lds = lds;
;     F.tid = threadIdx.x; F.lane = F.tid & 63; F.wave = readfirstlane_i(F.tid >> 6); F.G = gridDim.x; F.bid = blockIdx.x;
;     F.gw = F.bid * NWAVES + F.wave; F.NGW = F.G * NWAVES;
;     for (int u = F.tid; u < (LDS_BYTES - LDS_MISC) / 4; u += NTHREADS) ((LAS unsigned*)(lds + LDS_MISC))[u] = 0u;
;     __syncthreads();
;     XcdBarrier bar = xcd_barrier_post((unsigned*)(F.ws + WS_CTL), (volatile LAS unsigned*)(lds + LDS_MISC), F.wave);
_Z8mega_fwd4Args:
	s_load_dwordx2 s[100:101], s[0:1], 0x68
	s_waitcnt lgkmcnt(0)
	v_writelane_b32 v255, s100, 49
	v_writelane_b32 v255, s101, 50
	s_load_dwordx2 s[100:101], s[0:1], 0x128
	s_waitcnt lgkmcnt(0)
	v_writelane_b32 v255, s100, 53
	v_writelane_b32 v255, s101, 54
	s_load_dword s100, s[0:1], 0x130
	s_waitcnt lgkmcnt(0)
	v_writelane_b32 v255, s100, 51
	v_writelane_b32 v255, s2, 48
	s_mov_b32 s100, 0
	v_writelane_b32 v255, s100, 52
	s_nop 0
	s_load_dwordx4 s[4:7], s[0:1], 0x120
	s_load_dwordx8 s[8:15], s[0:1], 0x100
	s_mov_b32 s24, s2
	s_movk_i32 s2, 0x80
	v_cmp_gt_u32_e32 vcc, s2, v0
	s_waitcnt lgkmcnt(0)
	v_writelane_b32 v251, s4, 0
	s_nop 1
	v_writelane_b32 v251, s5, 1
	v_writelane_b32 v251, s6, 2
	v_writelane_b32 v251, s7, 3
	v_readfirstlane_b32 s6, v0
	s_and_saveexec_b64 s[2:3], vcc
	v_lshl_add_u32 v0, v0, 2, 0
	v_add_u32_e32 v0, 0x27e00, v0
	v_mov_b32_e32 v1, 0
	ds_write_b32 v0, v1
	v_writelane_b32 v251, s8, 4
	s_nop 1
	v_writelane_b32 v251, s9, 5
	v_writelane_b32 v251, s10, 6
	v_writelane_b32 v251, s11, 7
	v_writelane_b32 v251, s12, 8
	v_writelane_b32 v251, s13, 9
	v_writelane_b32 v251, s14, 10
	v_writelane_b32 v251, s15, 11
	s_or_b64 exec, exec, s[2:3]
	s_load_dword s96, s[0:1], 0x130
	s_load_dwordx16 s[44:59], s[0:1], 0x40
	s_load_dwordx16 s[8:23], s[0:1], 0x80
	s_waitcnt lgkmcnt(0)
	s_barrier
	s_getreg_b32 s2, hwreg(HW_REG_XCC_ID, 0, 4)
	v_writelane_b32 v251, s8, 12
	s_and_b32 s2, s2, 15
	s_cmp_gt_u32 s6, 63
	v_writelane_b32 v251, s9, 13
	v_writelane_b32 v251, s10, 14
	v_writelane_b32 v251, s11, 15
	v_writelane_b32 v251, s12, 16
	v_writelane_b32 v251, s13, 17
	v_writelane_b32 v251, s14, 18
	v_writelane_b32 v251, s15, 19
	v_writelane_b32 v251, s16, 20
	v_writelane_b32 v251, s17, 21
	v_writelane_b32 v251, s18, 22
	v_writelane_b32 v251, s19, 23
	v_writelane_b32 v251, s20, 24
	v_writelane_b32 v251, s21, 25
	v_writelane_b32 v251, s22, 26
	v_writelane_b32 v251, s23, 27
	v_writelane_b32 v251, s2, 28
	v_mbcnt_lo_u32_b32 v0, -1, 0
	s_cbranch_scc1 .LBB0_7
	v_mbcnt_hi_u32_b32 v1, -1, v0
	v_cmp_eq_u32_e32 vcc, 0, v1
	s_and_saveexec_b64 s[2:3], vcc
	s_cbranch_execz .LBB0_6
	s_mov_b64 s[4:5], exec
	v_mbcnt_lo_u32_b32 v1, s4, 0
	v_mbcnt_hi_u32_b32 v1, s5, v1
	v_cmp_eq_u32_e32 vcc, 0, v1
	s_and_b64 s[8:9], exec, vcc
	s_mov_b64 exec, s[8:9]
	s_cbranch_execz .LBB0_6
	s_load_dwordx4 s[8:11], s[0:1], 0x120
	v_readlane_b32 s7, v251, 28
	s_lshl_b32 s7, s7, 8
	s_bcnt1_i32_b64 s4, s[4:5]
	v_mov_b32_e32 v1, s7
	v_mov_b32_e32 v2, s4
	s_waitcnt lgkmcnt(0)
	global_atomic_add v1, v2, s[10:11] offset:1024

; #define LAS __attribute__((address_space(3)))
; #define NT_LOAD(p) __builtin_nontemporal_load(p)
; DEV void tr_item(const float* W, int ldw, int col0, int k0, bf16_t* WT, int K, int row0, LAS float* scr, int lane) {
; #pragma unroll 8
;     for (int i = 0; i < 32; ++i) { const int kk = 2 * i + (lane >> 5); scr[kk * 33 + (lane & 31)] = NT_LOAD(&W[(size_t)(k0 + kk) * ldw + col0 + (lane & 31)]); }
; DEV void phase_prologue_a(const Frame& F0) {
;     ...
;         constexpr int D_ITEMS = (FF / 64) * 32;
;         for (int it = F.gw; it < NE * D_ITEMS; it += F.NGW) { const int e = it / D_ITEMS, r = it % D_ITEMS, kb = r / 32, nb = r % 32;
;             tr_item(GIN(I_WDOWN) + ((size_t)l * NE + e) * FF * 1024, 1024, 32 * nb, 64 * kb, (bf16_t*)(F.ws + WS_WD) + ((size_t)l * NE + e) * 1024 * FF, FF, 32 * nb, scr, F.lane); }
.LBB0_29:
	s_andn2_b64 vcc, exec, s[12:13]
	s_cbranch_vccnz .LBB0_8
	s_cmp_eq_u32 s14, 0
	s_cbranch_scc1 .Lpro_dn_do
	v_readlane_b32 s100, v255, 51
	s_cmp_eq_u32 s100, 0x100
	s_cbranch_scc1 .LBB0_8
.Lpro_dn_do:
	s_lshl_b64 s[20:21], s[2:3], 4
	s_mov_b32 s2, s31
	s_mov_b64 s[40:41], 0x10000
	s_mov_b64 s[42:43], 0x8000
	v_add_u32_e32 v100, 0x400, v42
	v_add_u32_e32 v101, 0x840, v42
	v_add_u32_e32 v102, 0xc40, v42
	v_add_u32_e32 v103, 0x1080, v42
	v_add_u32_e32 v104, 0x1480, v42
	v_add_u32_e32 v105, 0x18c0, v42
	v_add_u32_e32 v106, 0x1cc0, v42
	s_ashr_i32 s22, s2, 31
	s_lshr_b32 s22, s22, 22
	s_add_i32 s22, s2, s22
	s_ashr_i32 s24, s22, 10
	s_and_b32 s22, s22, 0xfc00
	s_sub_i32 s22, s2, s22
	s_sext_i32_i16 s23, s22
	s_bfe_u32 s23, s23, 0x5001a
	s_add_i32 s23, s22, s23
	s_sext_i32_i16 s26, s23
	s_and_b32 s23, s23, 0xffe0
	s_sub_i32 s22, s22, s23
	s_sext_i32_i16 s22, s22
	s_lshl_b32 s22, s22, 5
	s_lshl_b32 s23, s26, 1
	s_ashr_i32 s25, s24, 31
	s_and_b32 s26, s23, 0xffffffc0
	s_ashr_i32 s23, s22, 31
	s_lshl_b64 s[28:29], s[24:25], 23
	s_lshl_b64 s[38:39], s[22:23], 2
	s_add_u32 s28, s38, s28
	v_add_u32_e32 v22, s26, v45
	s_addc_u32 s29, s39, s29
	v_add_u32_e32 v24, s26, v46
	v_add_u32_e32 v26, s26, v47
	v_add_u32_e32 v28, s26, v48
	v_add_u32_e32 v30, s26, v49
	v_add_u32_e32 v32, s26, v43
	v_add_u32_e32 v34, s26, v44
	s_ashr_i32 s27, s26, 31
	v_ashrrev_i32_e32 v23, 31, v22
	v_ashrrev_i32_e32 v25, 31, v24
	v_ashrrev_i32_e32 v27, 31, v26
	v_ashrrev_i32_e32 v29, 31, v28
	v_ashrrev_i32_e32 v31, 31, v30
	v_ashrrev_i32_e32 v33, 31, v32
	v_ashrrev_i32_e32 v35, 31, v34
	v_lshl_add_u64 v[36:37], v[2:3], 0, s[26:27]
	v_lshlrev_b64 v[22:23], 12, v[22:23]
	v_lshlrev_b64 v[24:25], 12, v[24:25]
	v_lshlrev_b64 v[26:27], 12, v[26:27]
	v_lshlrev_b64 v[28:29], 12, v[28:29]
	v_lshlrev_b64 v[30:31], 12, v[30:31]
	v_lshlrev_b64 v[32:33], 12, v[32:33]
	v_lshlrev_b64 v[34:35], 12, v[34:35]
	v_lshlrev_b64 v[36:37], 12, v[36:37]
	v_lshl_add_u64 v[22:23], s[28:29], 0, v[22:23]
	v_lshl_add_u64 v[24:25], s[28:29], 0, v[24:25]
	v_lshl_add_u64 v[26:27], s[28:29], 0, v[26:27]
	v_lshl_add_u64 v[28:29], s[28:29], 0, v[28:29]
	v_lshl_add_u64 v[30:31], s[28:29], 0, v[30:31]
	v_lshl_add_u64 v[32:33], s[28:29], 0, v[32:33]
	v_lshl_add_u64 v[34:35], s[28:29], 0, v[34:35]
	v_lshl_add_u64 v[36:37], s[28:29], 0, v[36:37]
	v_lshl_add_u64 v[22:23], v[16:17], 0, v[22:23]
	v_lshl_add_u64 v[24:25], v[16:17], 0, v[24:25]
	v_lshl_add_u64 v[26:27], v[16:17], 0, v[26:27]
	v_lshl_add_u64 v[28:29], v[16:17], 0, v[28:29]
	v_lshl_add_u64 v[30:31], v[16:17], 0, v[30:31]
	v_lshl_add_u64 v[32:33], v[16:17], 0, v[32:33]
	v_lshl_add_u64 v[34:35], v[16:17], 0, v[34:35]
	v_lshl_add_u64 v[36:37], v[16:17], 0, v[36:37]
	global_load_dword v68, v[36:37], off nt
	global_load_dword v69, v[34:35], off nt
	global_load_dword v70, v[32:33], off nt
	global_load_dword v71, v[30:31], off nt
	global_load_dword v72, v[28:29], off nt
	global_load_dword v73, v[26:27], off nt
	global_load_dword v74, v[24:25], off nt
	global_load_dword v75, v[22:23], off nt
	v_lshl_add_u64 v[36:37], v[36:37], 0, s[40:41]
	v_lshl_add_u64 v[34:35], v[34:35], 0, s[40:41]
	v_lshl_add_u64 v[32:33], v[32:33], 0, s[40:41]
	v_lshl_add_u64 v[30:31], v[30:31], 0, s[40:41]
	v_lshl_add_u64 v[28:29], v[28:29], 0, s[40:41]
	v_lshl_add_u64 v[26:27], v[26:27], 0, s[40:41]
	v_lshl_add_u64 v[24:25], v[24:25], 0, s[40:41]
	v_lshl_add_u64 v[22:23], v[22:23], 0, s[40:41]
	global_load_dword v76, v[36:37], off nt
	global_load_dword v77, v[34:35], off nt
	global_load_dword v78, v[32:33], off nt
	global_load_dword v79, v[30:31], off nt
	global_load_dword v80, v[28:29], off nt
	global_load_dword v81, v[26:27], off nt
	global_load_dword v82, v[24:25], off nt
	global_load_dword v83, v[22:23], off nt
	v_lshl_add_u64 v[36:37], v[36:37], 0, s[40:41]
	v_lshl_add_u64 v[34:35], v[34:35], 0, s[40:41]
	v_lshl_add_u64 v[32:33], v[32:33], 0, s[40:41]
	v_lshl_add_u64 v[30:31], v[30:31], 0, s[40:41]
	v_lshl_add_u64 v[28:29], v[28:29], 0, s[40:41]
	v_lshl_add_u64 v[26:27], v[26:27], 0, s[40:41]
	v_lshl_add_u64 v[24:25], v[24:25], 0, s[40:41]
	v_lshl_add_u64 v[22:23], v[22:23], 0, s[40:41]
	global_load_dword v84, v[36:37], off nt
	global_load_dword v85, v[34:35], off nt
	global_load_dword v86, v[32:33], off nt
	global_load_dword v87, v[30:31], off nt
	global_load_dword v88, v[28:29], off nt
	global_load_dword v89, v[26:27], off nt
	global_load_dword v90, v[24:25], off nt
	global_load_dword v91, v[22:23], off nt
	v_lshl_add_u64 v[36:37], v[36:37], 0, s[40:41]
	v_lshl_add_u64 v[34:35], v[34:35], 0, s[40:41]
	v_lshl_add_u64 v[32:33], v[32:33], 0, s[40:41]
	v_lshl_add_u64 v[30:31], v[30:31], 0, s[40:41]
	v_lshl_add_u64 v[28:29], v[28:29], 0, s[40:41]
	v_lshl_add_u64 v[26:27], v[26:27], 0, s[40:41]
	v_lshl_add_u64 v[24:25], v[24:25], 0, s[40:41]
	v_lshl_add_u64 v[22:23], v[22:23], 0, s[40:41]
	global_load_dword v92, v[36:37], off nt
	global_load_dword v93, v[34:35], off nt
	global_load_dword v94, v[32:33], off nt
	global_load_dword v95, v[30:31], off nt
	global_load_dword v96, v[28:29], off nt
	global_load_dword v97, v[26:27], off nt
	global_load_dword v98, v[24:25], off nt
	global_load_dword v99, v[22:23], off nt
	s_waitcnt vmcnt(0)

; #define WAVE_LDS_SYNC() do { int _z = 0; (void)emu::wave_xchg(&_z, 4); } while (0)
; #define LAS __attribute__((address_space(3)))
; #define WAVE_LDS_SYNC() asm volatile("s_waitcnt lgkmcnt(0)" ::: "memory")
; #define NT_LOAD(p) __builtin_nontemporal_load(p)
; #define NT_STORE(v, p) __builtin_nontemporal_store((v), (p))
; DEV unsigned pk2(float lo, float hi) { return f2bf(lo) | (f2bf(hi) << 16); }
; DEV unsigned pk2(float lo, float hi) { const f32x2n_t v = {lo, hi}; return __builtin_bit_cast(unsigned, __builtin_convertvector(v, bf16x2n_t)); }
; DEV void tr_item(const float* W, int ldw, int col0, int k0, bf16_t* WT, int K, int row0, LAS float* scr, int lane) {
; #pragma unroll 8
;     for (int i = 0; i < 32; ++i) { const int kk = 2 * i + (lane >> 5); scr[kk * 33 + (lane & 31)] = NT_LOAD(&W[(size_t)(k0 + kk) * ldw + col0 + (lane & 31)]); }
;     WAVE_LDS_SYNC();
;     const int c = lane & 7;
; #pragma unroll
;     for (int j = 0; j < 4; ++j) { const int n = (lane >> 3) + 8 * j; const LAS float* s = scr + (8 * c) * 33 + n;
;         u32x4 o; o.x = pk2(s[0 * 33], s[1 * 33]); o.y = pk2(s[2 * 33], s[3 * 33]); o.z = pk2(s[4 * 33], s[5 * 33]); o.w = pk2(s[6 * 33], s[7 * 33]);
;         NT_STORE(o, (u32x4*)(WT + (size_t)(row0 + n) * K + k0 + 8 * c)); }
; DEV void phase_prologue_a(const Frame& F0) {
;     ...
;         constexpr int D_ITEMS = (FF / 64) * 32;
;         for (int it = F.gw; it < NE * D_ITEMS; it += F.NGW) { const int e = it / D_ITEMS, r = it % D_ITEMS, kb = r / 32, nb = r % 32;
;             tr_item(GIN(I_WDOWN) + ((size_t)l * NE + e) * FF * 1024, 1024, 32 * nb, 64 * kb, (bf16_t*)(F.ws + WS_WD) + ((size_t)l * NE + e) * 1024 * FF, FF, 32 * nb, scr, F.lane); }
.LBB0_1828:
	s_waitcnt vmcnt(0)
	s_mov_b64 s[52:53], 0x1000
	v_readlane_b32 s48, v253, 49
	s_barrier
	v_readlane_b32 s3, v255, 52
	s_add_i32 s0, s3, 1
	v_writelane_b32 v255, s0, 52
	s_cmp_gt_u32 s0, 3
	s_cbranch_scc1 .Lslot_done
	v_readlane_b32 s2, v255, 51
	s_cmp_lg_u32 s2, 0x100
	s_cbranch_scc1 .Lslot_done
	v_readlane_b32 s2, v255, 48
	s_cmp_lt_u32 s2, 64
	s_cbranch_scc1 .Lslot_done
	v_readlane_b32 s3, v251, 29
	s_sub_i32 s2, s2, 64
	s_lshl_b32 s2, s2, 3
	s_add_i32 s2, s2, s3
	v_readlane_b32 s4, v255, 49
	v_readlane_b32 s5, v255, 50
	v_readlane_b32 s6, v255, 53
	v_readlane_b32 s7, v255, 54
	s_add_u32 s6, s6, 0x22bc8000
	s_addc_u32 s7, s7, 0
	s_lshl_b32 s8, s0, 27
	s_add_u32 s4, s4, s8
	s_addc_u32 s5, s5, 0
	s_lshl_b32 s8, s0, 26
	s_add_u32 s6, s6, s8
	s_addc_u32 s7, s7, 0
	s_lshl_b32 s30, s3, 14
	v_and_b32_e32 v120, 31, v200
	v_lshlrev_b32_e32 v2, 2, v120
	v_lshrrev_b32_e32 v3, 5, v200
	v_and_b32_e32 v4, 7, v200
	v_lshrrev_b32_e32 v6, 3, v200
	v_mul_u32_u24_e32 v7, 33, v3
	v_add_u32_e32 v7, v7, v120
	v_lshl_add_u32 v7, v7, 2, s30
	v_add_u32_e32 v8, 0x400, v7
	v_add_u32_e32 v9, 0x840, v7
	v_add_u32_e32 v10, 0xc40, v7
	v_add_u32_e32 v11, 0x1080, v7
	v_add_u32_e32 v12, 0x1480, v7
	v_add_u32_e32 v13, 0x18c0, v7
	v_add_u32_e32 v14, 0x1cc0, v7
	v_mul_u32_u24_e32 v120, 0x108, v4
	v_add_u32_e32 v120, v120, v6
	v_lshl_add_u32 v15, v120, 2, s30
	v_lshl_add_u32 v122, v3, 12, v2
	v_mov_b32_e32 v123, 0
	v_lshlrev_b32_e32 v124, 4, v4
	v_lshl_add_u32 v124, v6, 12, v124
	v_mov_b32_e32 v125, 0
	s_mov_b64 s[40:41], 0x10000
	s_mov_b64 s[42:43], 0x8000
	s_mov_b64 s[44:45], 0x2000
.Lslot_loop:
	s_lshr_b32 s8, s2, 10
	s_and_b32 s9, s2, 0x3ff
	s_lshr_b32 s10, s9, 5
	s_and_b32 s9, s9, 31
	s_lshl_b32 s24, s10, 18
	s_lshl_b32 s25, s9, 7
	s_add_i32 s24, s24, s25
	s_lshr_b32 s29, s8, 9
	s_lshl_b32 s28, s8, 23
	s_add_u32 s28, s28, s24
	s_addc_u32 s29, s29, 0
	s_add_u32 s28, s28, s4
	s_addc_u32 s29, s29, s5
	s_lshl_b32 s24, s9, 17
	s_lshl_b32 s25, s10, 7
	s_add_i32 s24, s24, s25
	s_lshr_b32 s11, s8, 10
	s_lshl_b32 s10, s8, 22
	s_add_u32 s10, s10, s24
	s_addc_u32 s11, s11, 0
	s_add_u32 s10, s10, s6
	s_addc_u32 s11, s11, s7
	v_lshl_add_u64 v[16:17], s[28:29], 0, v[122:123]
	v_lshl_add_u64 v[18:19], v[16:17], 0, s[44:45]
	v_lshl_add_u64 v[20:21], v[18:19], 0, s[44:45]
	v_lshl_add_u64 v[22:23], v[20:21], 0, s[44:45]
	v_lshl_add_u64 v[24:25], v[22:23], 0, s[44:45]
	v_lshl_add_u64 v[26:27], v[24:25], 0, s[44:45]
	v_lshl_add_u64 v[28:29], v[26:27], 0, s[44:45]
	v_lshl_add_u64 v[30:31], v[28:29], 0, s[44:45]
	global_load_dword v32, v[16:17], off nt
	global_load_dword v33, v[18:19], off nt
	global_load_dword v34, v[20:21], off nt
	global_load_dword v35, v[22:23], off nt
	global_load_dword v36, v[24:25], off nt
	global_load_dword v37, v[26:27], off nt
	global_load_dword v38, v[28:29], off nt
	global_load_dword v39, v[30:31], off nt
	v_lshl_add_u64 v[16:17], v[16:17], 0, s[40:41]
	v_lshl_add_u64 v[18:19], v[18:19], 0, s[40:41]
	v_lshl_add_u64 v[20:21], v[20:21], 0, s[40:41]
	v_lshl_add_u64 v[22:23], v[22:23], 0, s[40:41]
	v_lshl_add_u64 v[24:25], v[24:25], 0, s[40:41]
	v_lshl_add_u64 v[26:27], v[26:27], 0, s[40:41]
	v_lshl_add_u64 v[28:29], v[28:29], 0, s[40:41]
	v_lshl_add_u64 v[30:31], v[30:31], 0, s[40:41]
	global_load_dword v40, v[16:17], off nt
	global_load_dword v41, v[18:19], off nt
	global_load_dword v42, v[20:21], off nt
	global_load_dword v43, v[22:23], off nt
	global_load_dword v44, v[24:25], off nt
	global_load_dword v45, v[26:27], off nt
	global_load_dword v46, v[28:29], off nt
	global_load_dword v47, v[30:31], off nt
	v_lshl_add_u64 v[16:17], v[16:17], 0, s[40:41]
	v_lshl_add_u64 v[18:19], v[18:19], 0, s[40:41]
	v_lshl_add_u64 v[20:21], v[20:21], 0, s[40:41]
	v_lshl_add_u64 v[22:23], v[22:23], 0, s[40:41]
	v_lshl_add_u64 v[24:25], v[24:25], 0, s[40:41]
	v_lshl_add_u64 v[26:27], v[26:27], 0, s[40:41]
	v_lshl_add_u64 v[28:29], v[28:29], 0, s[40:41]
	v_lshl_add_u64 v[30:31], v[30:31], 0, s[40:41]
	global_load_dword v48, v[16:17], off nt
	global_load_dword v49, v[18:19], off nt
	global_load_dword v50, v[20:21], off nt
	global_load_dword v51, v[22:23], off nt
	global_load_dword v52, v[24:25], off nt
	global_load_dword v53, v[26:27], off nt
	global_load_dword v54, v[28:29], off nt
	global_load_dword v55, v[30:31], off nt
	v_lshl_add_u64 v[16:17], v[16:17], 0, s[40:41]
	v_lshl_add_u64 v[18:19], v[18:19], 0, s[40:41]
	v_lshl_add_u64 v[20:21], v[20:21], 0, s[40:41]
	v_lshl_add_u64 v[22:23], v[22:23], 0, s[40:41]
	v_lshl_add_u64 v[24:25], v[24:25], 0, s[40:41]
	v_lshl_add_u64 v[26:27], v[26:27], 0, s[40:41]
	v_lshl_add_u64 v[28:29], v[28:29], 0, s[40:41]
	v_lshl_add_u64 v[30:31], v[30:31], 0, s[40:41]
	global_load_dword v56, v[16:17], off nt
	global_load_dword v57, v[18:19], off nt
	global_load_dword v58, v[20:21], off nt
	global_load_dword v59, v[22:23], off nt
	global_load_dword v60, v[24:25], off nt
	global_load_dword v61, v[26:27], off nt
	global_load_dword v62, v[28:29], off nt
	global_load_dword v63, v[30:31], off nt
	v_lshl_add_u64 v[64:65], s[10:11], 0, v[124:125]
	v_lshl_add_u64 v[66:67], v[64:65], 0, s[42:43]
	v_lshl_add_u64 v[68:69], v[66:67], 0, s[42:43]
	v_lshl_add_u64 v[70:71], v[68:69], 0, s[42:43]
	s_waitcnt vmcnt(30)
; #define WAVE_LDS_SYNC() do { int _z = 0; (void)emu::wave_xchg(&_z, 4); } while (0)
; #define LAS __attribute__((address_space(3)))
; #define WAVE_LDS_SYNC() asm volatile("s_waitcnt lgkmcnt(0)" ::: "memory")
; #define NT_LOAD(p) __builtin_nontemporal_load(p)
; #define NT_STORE(v, p) __builtin_nontemporal_store((v), (p))
; DEV unsigned pk2(float lo, float hi) { return f2bf(lo) | (f2bf(hi) << 16); }
; DEV unsigned pk2(float lo, float hi) { const f32x2n_t v = {lo, hi}; return __builtin_bit_cast(unsigned, __builtin_convertvector(v, bf16x2n_t)); }
; DEV void tr_item(const float* W, int ldw, int col0, int k0, bf16_t* WT, int K, int row0, LAS float* scr, int lane) {
; #pragma unroll 8
;     for (int i = 0; i < 32; ++i) { const int kk = 2 * i + (lane >> 5); scr[kk * 33 + (lane & 31)] = NT_LOAD(&W[(size_t)(k0 + kk) * ldw + col0 + (lane & 31)]); }
;     WAVE_LDS_SYNC();
;     const int c = lane & 7;
; #pragma unroll
;     for (int j = 0; j < 4; ++j) { const int n = (lane >> 3) + 8 * j; const LAS float* s = scr + (8 * c) * 33 + n;
;         u32x4 o; o.x = pk2(s[0 * 33], s[1 * 33]); o.y = pk2(s[2 * 33], s[3 * 33]); o.z = pk2(s[4 * 33], s[5 * 33]); o.w = pk2(s[6 * 33], s[7 * 33]);
;         NT_STORE(o, (u32x4*)(WT + (size_t)(row0 + n) * K + k0 + 8 * c)); }
;     WAVE_LDS_SYNC();
	ds_write2_b32 v7, v32, v33 offset1:66
	s_waitcnt vmcnt(28)
	ds_write2_b32 v7, v34, v35 offset0:132 offset1:198
	s_waitcnt vmcnt(26)
	ds_write2_b32 v8, v36, v37 offset0:8 offset1:74
	s_waitcnt vmcnt(24)
	ds_write2_b32 v8, v38, v39 offset0:140 offset1:206
	s_waitcnt vmcnt(22)
	ds_write2_b32 v9, v40, v41 offset1:66
	s_waitcnt vmcnt(20)
	ds_write2_b32 v9, v42, v43 offset0:132 offset1:198
	s_waitcnt vmcnt(18)
	ds_write2_b32 v10, v44, v45 offset0:8 offset1:74
	s_waitcnt vmcnt(16)
	ds_write2_b32 v10, v46, v47 offset0:140 offset1:206
	s_waitcnt vmcnt(14)
	ds_write2_b32 v11, v48, v49 offset1:66
	s_waitcnt vmcnt(12)
	ds_write2_b32 v11, v50, v51 offset0:132 offset1:198
	s_waitcnt vmcnt(10)
	ds_write2_b32 v12, v52, v53 offset0:8 offset1:74
	s_waitcnt vmcnt(8)
	ds_write2_b32 v12, v54, v55 offset0:140 offset1:206
	s_waitcnt vmcnt(6)
	ds_write2_b32 v13, v56, v57 offset1:66
	s_waitcnt vmcnt(4)
	ds_write2_b32 v13, v58, v59 offset0:132 offset1:198
	s_waitcnt vmcnt(2)
	ds_write2_b32 v14, v60, v61 offset0:8 offset1:74
	s_waitcnt vmcnt(0)
	ds_write2_b32 v14, v62, v63 offset0:140 offset1:206
	ds_read2_b32 v[72:73], v15 offset1:8
	ds_read2_b32 v[74:75], v15 offset0:33 offset1:41
	ds_read2_b32 v[76:77], v15 offset0:66 offset1:74
	ds_read2_b32 v[78:79], v15 offset0:99 offset1:107
	ds_read2_b32 v[80:81], v15 offset0:132 offset1:140
	ds_read2_b32 v[82:83], v15 offset0:165 offset1:173
	ds_read2_b32 v[84:85], v15 offset0:198 offset1:206
	ds_read2_b32 v[86:87], v15 offset0:231 offset1:239
	ds_read2_b32 v[88:89], v15 offset0:16 offset1:24
	ds_read2_b32 v[90:91], v15 offset0:49 offset1:57
	ds_read2_b32 v[92:93], v15 offset0:82 offset1:90
	ds_read2_b32 v[94:95], v15 offset0:115 offset1:123
	s_waitcnt lgkmcnt(4)
	v_cvt_pk_bf16_f32 v104, v72, v74
	v_cvt_pk_bf16_f32 v105, v76, v78
	v_cvt_pk_bf16_f32 v106, v80, v82
	v_cvt_pk_bf16_f32 v107, v84, v86
	v_cvt_pk_bf16_f32 v108, v73, v75
	v_cvt_pk_bf16_f32 v109, v77, v79
	v_cvt_pk_bf16_f32 v110, v81, v83
	v_cvt_pk_bf16_f32 v111, v85, v87
	ds_read2_b32 v[96:97], v15 offset0:148 offset1:156
	ds_read2_b32 v[98:99], v15 offset0:181 offset1:189
	ds_read2_b32 v[100:101], v15 offset0:214 offset1:222
	ds_read2_b32 v[102:103], v15 offset0:247 offset1:255
	global_store_dwordx4 v[64:65], v[104:107], off nt
	global_store_dwordx4 v[66:67], v[108:111], off nt
	s_waitcnt lgkmcnt(0)
	v_cvt_pk_bf16_f32 v112, v88, v90
	v_cvt_pk_bf16_f32 v113, v92, v94
	v_cvt_pk_bf16_f32 v114, v96, v98
	v_cvt_pk_bf16_f32 v115, v100, v102
	v_cvt_pk_bf16_f32 v116, v89, v91
	v_cvt_pk_bf16_f32 v117, v93, v95
	v_cvt_pk_bf16_f32 v118, v97, v99
	v_cvt_pk_bf16_f32 v119, v101, v103
	global_store_dwordx4 v[68:69], v[112:115], off nt
	global_store_dwordx4 v[70:71], v[116:119], off nt
	s_addk_i32 s2, 0x600
	s_cmp_lt_u32 s2, 0x4000
	s_cbranch_scc1 .Lslot_loop
.Lslot_done:
.LBB0_1829:
	s_waitcnt vmcnt(0)
	v_readlane_b32 s0, v251, 29
	s_barrier
	s_nop 0
	v_or_b32_e32 v0, s0, v200
	v_cmp_eq_u32_e32 vcc, 0, v0
	s_and_saveexec_b64 s[34:35], vcc
	s_cbranch_execz .LBB0_1873
	v_readlane_b32 s4, v251, 0
	v_readlane_b32 s6, v251, 2
	v_readlane_b32 s7, v251, 3
	s_mov_b64 s[36:37], s[6:7]
	v_readlane_b32 s0, v251, 28
	v_readlane_b32 s2, v253, 7
	s_waitcnt vmcnt(0) lgkmcnt(0)
	v_readlane_b32 s5, v251, 1
	s_nop 0
	v_mov_b32_e32 v0, s2
	ds_read_b32 v2, v0
	v_readlane_b32 s2, v253, 8
	s_waitcnt lgkmcnt(0)
	v_cmp_ne_u32_e32 vcc, 0, v2
	v_mov_b32_e32 v0, s2
	ds_read_b32 v0, v0
	s_cbranch_vccnz .LBB0_1844
	s_add_u32 s2, s36, 0x1000
	s_addc_u32 s3, s37, 0
	s_add_u32 s4, s36, 0x1100
	s_addc_u32 s5, s37, 0
	s_add_u32 s6, s36, 0x1200
	s_addc_u32 s7, s37, 0
	s_add_u32 s8, s36, 0x1300
	s_addc_u32 s9, s37, 0
	s_mov_b32 s28, 1
	s_mov_b64 s[10:11], 0
	s_branch .LBB0_1834
